# P2 K-loop as well: LDS-DMA loads on SGPR bases (16 v_lshl_add_u64 per iteration removed); P8 K-loop already converted
# baseline (speedup 1.0000x reference)
; #define PG8_STAGE(bufoff, gbase, voff) do { _Pragma("unroll") for (int _i = 0; _i < 2; ++_i) \
;         __builtin_amdgcn_global_load_lds((const unsigned*)((const char*)(gbase) + (voff)[_i]), (PG8_LAS unsigned*)(lds + (bufoff) + ldsw + _i * 8192), 16, 0, 0); } while (0)
; #define PG8_LDA(dst, b, h) do { _Pragma("unroll") for (int m = 0; m < 4; ++m) _Pragma("unroll") for (int k = 0; k < 2; ++k) dst[m][k] = *(const PG8_LAS bf16x8*)(lds + PG8_SA(b, h) + aoff + m * 2048 + k * 1024); } while (0)
; #define PG8_LDB(dst, b, h) do { _Pragma("unroll") for (int n = 0; n < 2; ++n) _Pragma("unroll") for (int k = 0; k < 2; ++k) dst[n][k] = *(const PG8_LAS bf16x8*)(lds + PG8_SB(b, h) + boff + n * 2048 + k * 1024); } while (0)
; #define PG8_MMA(ai, bj, At, Bt) do { __builtin_amdgcn_s_setprio(1); _Pragma("unroll") for (int m = 0; m < 4; ++m) _Pragma("unroll") for (int n = 0; n < 2; ++n) _Pragma("unroll") for (int k = 0; k < 2; ++k) \
;         acc[ai][bj][m][n] = __builtin_amdgcn_mfma_f32_16x16x32_bf16(Bt[n][k], At[m][k], acc[ai][bj][m][n], 0, 0, 0); __builtin_amdgcn_s_setprio(0); } while (0)
; #define PG8_WAIT_V(n) asm volatile("s_waitcnt vmcnt(" #n ")" ::: "memory")
; template <class Epi, class Sched, bool ALIGN_EPI = false, bool SP2 = false>
; __device__ __forceinline__ void gemm_phase(PG8_LAS unsigned char* lds, const Gemm g, const Sched& S, const Epi& E) {
;     ...
;             PG8_LDB(B0, 0, 0); PG8_LDB(B1, 0, 1); PG8_SCHED; PG8_LDA(At, 0, 0); PG8_STAGE(PG8_SA(1, 1), a1 + hstep, voffA);
;             PG8_WAIT_V(8); PG8_WAIT_L(0); PG8_BAR; PG8_MMA(0, 0, At, B0); PG8_MMA(0, 1, At, B1); PG8_BAR; PG8_SCHED;
;             PG8_LDA(At, 0, 1); PG8_STAGE(PG8_SB(0, 0), b2, voffB); PG8_STAGE(PG8_SB(0, 1), b2 + hstep, voffB); PG8_STAGE(PG8_SA(0, 0), a2, voffA);
;             PG8_WAIT_V(8); PG8_WAIT_L(0); PG8_BAR; PG8_MMA(1, 0, At, B0); PG8_MMA(1, 1, At, B1); PG8_BAR; PG8_SCHED;
;             PG8_LDB(B0, 1, 0); PG8_LDB(B1, 1, 1); PG8_SCHED; PG8_LDA(At, 1, 0); PG8_STAGE(PG8_SA(0, 1), a2 + hstep, voffA);
;             PG8_WAIT_V(8); PG8_WAIT_L(0); PG8_BAR; PG8_MMA(0, 0, At, B0); PG8_MMA(0, 1, At, B1); PG8_BAR; PG8_SCHED;
;             PG8_LDA(At, 1, 1); PG8_STAGE(PG8_SB(1, 0), b3, voffB); PG8_STAGE(PG8_SB(1, 1), b3 + hstep, voffB); PG8_STAGE(PG8_SA(1, 0), a3, voffA);
;             PG8_WAIT_V(8); PG8_WAIT_L(0); PG8_BAR; PG8_MMA(1, 0, At, B0); PG8_MMA(1, 1, At, B1); PG8_BAR; PG8_SCHED;
.LBB0_270:
	ds_read_b128 v[146:149], v152
	ds_read_b128 v[156:159], v152 offset:1024
	ds_read_b128 v[160:163], v152 offset:2048
	ds_read_b128 v[164:167], v152 offset:3072
	ds_read_b128 v[168:171], v153
	ds_read_b128 v[172:175], v153 offset:1024
	ds_read_b128 v[176:179], v153 offset:2048
	ds_read_b128 v[180:183], v153 offset:3072
	s_add_u32 s3, s88, 0xfffc0080
	s_addc_u32 s90, s89, -1
	s_cmp_eq_u32 s96, 12
	s_cselect_b32 s93, s0, s90
	s_cselect_b32 s92, s1, s3
	s_cselect_b32 s91, s7, s87
	s_cselect_b32 s90, s69, s81
	s_add_i32 m0, s13, 0xc000
	ds_read_b128 v[184:187], v154
	ds_read_b128 v[188:191], v154 offset:1024
	ds_read_b128 v[192:195], v154 offset:2048
	ds_read_b128 v[196:199], v154 offset:3072
	ds_read_b128 v[200:203], v154 offset:4096
	ds_read_b128 v[204:207], v154 offset:5120
	ds_read_b128 v[208:211], v154 offset:6144
	ds_read_b128 v[212:215], v154 offset:7168
	global_load_lds_dwordx4 v138, s[88:89]
	s_add_i32 m0, s13, 0xe000
	s_nop 0
	global_load_lds_dwordx4 v140, s[88:89]
	s_waitcnt vmcnt(8)
	s_waitcnt lgkmcnt(0)
	s_barrier
	s_setprio 1
	s_waitcnt lgkmcnt(0)
	v_mfma_f32_16x16x32_bf16 v[126:129], v[146:149], v[184:187], v[126:129]
	v_mfma_f32_16x16x32_bf16 v[122:125], v[160:163], v[184:187], v[122:125]
	v_mfma_f32_16x16x32_bf16 v[118:121], v[146:149], v[192:195], v[118:121]
	v_mfma_f32_16x16x32_bf16 v[114:117], v[160:163], v[192:195], v[114:117]
	v_mfma_f32_16x16x32_bf16 v[110:113], v[146:149], v[200:203], v[110:113]
	v_mfma_f32_16x16x32_bf16 v[106:109], v[160:163], v[200:203], v[106:109]
	v_mfma_f32_16x16x32_bf16 v[102:105], v[146:149], v[208:211], v[102:105]
	v_mfma_f32_16x16x32_bf16 v[98:101], v[160:163], v[208:211], v[98:101]
	v_mfma_f32_16x16x32_bf16 v[126:129], v[156:159], v[188:191], v[126:129]
	v_mfma_f32_16x16x32_bf16 v[122:125], v[164:167], v[188:191], v[122:125]
	v_mfma_f32_16x16x32_bf16 v[118:121], v[156:159], v[196:199], v[118:121]
	v_mfma_f32_16x16x32_bf16 v[114:117], v[164:167], v[196:199], v[114:117]
	v_mfma_f32_16x16x32_bf16 v[110:113], v[156:159], v[204:207], v[110:113]
	v_mfma_f32_16x16x32_bf16 v[106:109], v[164:167], v[204:207], v[106:109]
	v_mfma_f32_16x16x32_bf16 v[102:105], v[156:159], v[212:215], v[102:105]
	v_mfma_f32_16x16x32_bf16 v[98:101], v[164:167], v[212:215], v[98:101]
	s_setprio 0
	s_setprio 1
	v_mfma_f32_16x16x32_bf16 v[62:65], v[168:171], v[184:187], v[62:65]
	v_mfma_f32_16x16x32_bf16 v[58:61], v[176:179], v[184:187], v[58:61]
	v_mfma_f32_16x16x32_bf16 v[54:57], v[168:171], v[192:195], v[54:57]
	v_mfma_f32_16x16x32_bf16 v[50:53], v[176:179], v[192:195], v[50:53]
	v_mfma_f32_16x16x32_bf16 v[46:49], v[168:171], v[200:203], v[46:49]
	v_mfma_f32_16x16x32_bf16 v[42:45], v[176:179], v[200:203], v[42:45]
	v_mfma_f32_16x16x32_bf16 v[38:41], v[168:171], v[208:211], v[38:41]
	v_mfma_f32_16x16x32_bf16 v[34:37], v[176:179], v[208:211], v[34:37]
	v_mfma_f32_16x16x32_bf16 v[62:65], v[172:175], v[188:191], v[62:65]
	v_mfma_f32_16x16x32_bf16 v[58:61], v[180:183], v[188:191], v[58:61]
	v_mfma_f32_16x16x32_bf16 v[54:57], v[172:175], v[196:199], v[54:57]
	v_mfma_f32_16x16x32_bf16 v[50:53], v[180:183], v[196:199], v[50:53]
	v_mfma_f32_16x16x32_bf16 v[46:49], v[172:175], v[204:207], v[46:49]
	v_mfma_f32_16x16x32_bf16 v[42:45], v[180:183], v[204:207], v[42:45]
	v_mfma_f32_16x16x32_bf16 v[38:41], v[172:175], v[212:215], v[38:41]
	v_mfma_f32_16x16x32_bf16 v[34:37], v[180:183], v[212:215], v[34:37]
	s_setprio 0
	s_barrier
	s_add_i32 s3, s33, s12
	s_mov_b32 m0, s3
	ds_read_b128 v[184:187], v154 offset:16384
	ds_read_b128 v[188:191], v154 offset:17408
	ds_read_b128 v[192:195], v154 offset:18432
	ds_read_b128 v[196:199], v154 offset:19456
	ds_read_b128 v[200:203], v154 offset:20480
	ds_read_b128 v[204:207], v154 offset:21504
	ds_read_b128 v[208:211], v154 offset:22528
	ds_read_b128 v[212:215], v154 offset:23552
	global_load_lds_dwordx4 v132, s[90:91]
	s_add_i32 m0, s3, 0x2000
	s_add_u32 vcc_lo, s90, 0x40000
	s_addc_u32 vcc_hi, s91, 0
	s_add_i32 s3, s75, s12
	global_load_lds_dwordx4 v136, s[90:91]
	s_mov_b32 m0, s3
	global_load_lds_dwordx4 v132, vcc
	s_add_i32 m0, s3, 0x2000
	s_nop 0
	global_load_lds_dwordx4 v136, vcc
	s_mov_b32 m0, s13
	s_nop 0
	global_load_lds_dwordx4 v130, s[92:93]
	s_mov_b32 m0, s34
	s_nop 0
	global_load_lds_dwordx4 v134, s[92:93]
	s_waitcnt vmcnt(8)
	s_waitcnt lgkmcnt(0)
	s_barrier
	s_setprio 1
	s_waitcnt lgkmcnt(0)
	v_mfma_f32_16x16x32_bf16 v[94:97], v[146:149], v[184:187], v[94:97]
	v_mfma_f32_16x16x32_bf16 v[90:93], v[160:163], v[184:187], v[90:93]
	v_mfma_f32_16x16x32_bf16 v[86:89], v[146:149], v[192:195], v[86:89]
	v_mfma_f32_16x16x32_bf16 v[82:85], v[160:163], v[192:195], v[82:85]
	v_mfma_f32_16x16x32_bf16 v[78:81], v[146:149], v[200:203], v[78:81]
	v_mfma_f32_16x16x32_bf16 v[74:77], v[160:163], v[200:203], v[74:77]
	v_mfma_f32_16x16x32_bf16 v[70:73], v[146:149], v[208:211], v[70:73]
	v_mfma_f32_16x16x32_bf16 v[66:69], v[160:163], v[208:211], v[66:69]
	v_mfma_f32_16x16x32_bf16 v[94:97], v[156:159], v[188:191], v[94:97]
	v_mfma_f32_16x16x32_bf16 v[90:93], v[164:167], v[188:191], v[90:93]
	v_mfma_f32_16x16x32_bf16 v[86:89], v[156:159], v[196:199], v[86:89]
	v_mfma_f32_16x16x32_bf16 v[82:85], v[164:167], v[196:199], v[82:85]
	v_mfma_f32_16x16x32_bf16 v[78:81], v[156:159], v[204:207], v[78:81]
	v_mfma_f32_16x16x32_bf16 v[74:77], v[164:167], v[204:207], v[74:77]
	v_mfma_f32_16x16x32_bf16 v[70:73], v[156:159], v[212:215], v[70:73]
	v_mfma_f32_16x16x32_bf16 v[66:69], v[164:167], v[212:215], v[66:69]
	s_setprio 0
	s_setprio 1
	v_mfma_f32_16x16x32_bf16 v[30:33], v[168:171], v[184:187], v[30:33]
	v_mfma_f32_16x16x32_bf16 v[26:29], v[176:179], v[184:187], v[26:29]
	v_mfma_f32_16x16x32_bf16 v[22:25], v[168:171], v[192:195], v[22:25]
	v_mfma_f32_16x16x32_bf16 v[18:21], v[176:179], v[192:195], v[18:21]
	v_mfma_f32_16x16x32_bf16 v[14:17], v[168:171], v[200:203], v[14:17]
	v_mfma_f32_16x16x32_bf16 v[10:13], v[176:179], v[200:203], v[10:13]
	v_mfma_f32_16x16x32_bf16 v[6:9], v[168:171], v[208:211], v[6:9]
	v_mfma_f32_16x16x32_bf16 v[2:5], v[176:179], v[208:211], v[2:5]
	v_mfma_f32_16x16x32_bf16 v[30:33], v[172:175], v[188:191], v[30:33]
	v_mfma_f32_16x16x32_bf16 v[26:29], v[180:183], v[188:191], v[26:29]
	v_mfma_f32_16x16x32_bf16 v[22:25], v[172:175], v[196:199], v[22:25]
	v_mfma_f32_16x16x32_bf16 v[18:21], v[180:183], v[196:199], v[18:21]
	v_mfma_f32_16x16x32_bf16 v[14:17], v[172:175], v[204:207], v[14:17]
	v_mfma_f32_16x16x32_bf16 v[10:13], v[180:183], v[204:207], v[10:13]
	v_mfma_f32_16x16x32_bf16 v[6:9], v[172:175], v[212:215], v[6:9]
	v_mfma_f32_16x16x32_bf16 v[2:5], v[180:183], v[212:215], v[2:5]
	s_setprio 0
	s_barrier
; #define PG8_STAGE(bufoff, gbase, voff) do { _Pragma("unroll") for (int _i = 0; _i < 2; ++_i) \
;         __builtin_amdgcn_global_load_lds((const unsigned*)((const char*)(gbase) + (voff)[_i]), (PG8_LAS unsigned*)(lds + (bufoff) + ldsw + _i * 8192), 16, 0, 0); } while (0)
; #define PG8_LDA(dst, b, h) do { _Pragma("unroll") for (int m = 0; m < 4; ++m) _Pragma("unroll") for (int k = 0; k < 2; ++k) dst[m][k] = *(const PG8_LAS bf16x8*)(lds + PG8_SA(b, h) + aoff + m * 2048 + k * 1024); } while (0)
; #define PG8_LDB(dst, b, h) do { _Pragma("unroll") for (int n = 0; n < 2; ++n) _Pragma("unroll") for (int k = 0; k < 2; ++k) dst[n][k] = *(const PG8_LAS bf16x8*)(lds + PG8_SB(b, h) + boff + n * 2048 + k * 1024); } while (0)
; #define PG8_MMA(ai, bj, At, Bt) do { __builtin_amdgcn_s_setprio(1); _Pragma("unroll") for (int m = 0; m < 4; ++m) _Pragma("unroll") for (int n = 0; n < 2; ++n) _Pragma("unroll") for (int k = 0; k < 2; ++k) \
;         acc[ai][bj][m][n] = __builtin_amdgcn_mfma_f32_16x16x32_bf16(Bt[n][k], At[m][k], acc[ai][bj][m][n], 0, 0, 0); __builtin_amdgcn_s_setprio(0); } while (0)
; #define PG8_WAIT_V(n) asm volatile("s_waitcnt vmcnt(" #n ")" ::: "memory")
; #define PG8_WAIT_L(n) asm volatile("s_waitcnt lgkmcnt(" #n ")" ::: "memory")
; #define PG8_BAR __builtin_amdgcn_s_barrier()
; #define PG8_SCHED __builtin_amdgcn_sched_barrier(0)
; template <class Epi, class Sched, bool ALIGN_EPI = false, bool SP2 = false>
; __device__ __forceinline__ void gemm_phase(PG8_LAS unsigned char* lds, const Gemm g, const Sched& S, const Epi& E) {
;     ...
;             PG8_LDB(B0, 1, 0); PG8_LDB(B1, 1, 1); PG8_SCHED; PG8_LDA(At, 1, 0); PG8_STAGE(PG8_SA(0, 1), a2 + hstep, voffA);
;             PG8_WAIT_V(8); PG8_WAIT_L(0); PG8_BAR; PG8_MMA(0, 0, At, B0); PG8_MMA(0, 1, At, B1); PG8_BAR; PG8_SCHED;
;             PG8_LDA(At, 1, 1); PG8_STAGE(PG8_SB(1, 0), b3, voffB); PG8_STAGE(PG8_SB(1, 1), b3 + hstep, voffB); PG8_STAGE(PG8_SA(1, 0), a3, voffA);
;             PG8_WAIT_V(8); PG8_WAIT_L(0); PG8_BAR; PG8_MMA(1, 0, At, B0); PG8_MMA(1, 1, At, B1); PG8_BAR; PG8_SCHED;
	s_add_i32 s3, 0, 0x18000
	s_add_i32 s97, 0, 0x1c000
	v_add_u32_e32 v164, s3, v150
	v_add_u32_e32 v180, s97, v150
	ds_read_b128 v[146:149], v164
	ds_read_b128 v[156:159], v164 offset:1024
	ds_read_b128 v[160:163], v164 offset:2048
	ds_read_b128 v[164:167], v164 offset:3072
	ds_read_b128 v[168:171], v180
	ds_read_b128 v[172:175], v180 offset:1024
	ds_read_b128 v[176:179], v180 offset:2048
	ds_read_b128 v[180:183], v180 offset:3072
	s_add_u32 s92, s92, 0x40000
	s_addc_u32 s93, s93, 0
	s_mov_b32 m0, s35
	ds_read_b128 v[184:187], v154 offset:32768
	ds_read_b128 v[188:191], v154 offset:33792
	ds_read_b128 v[192:195], v154 offset:34816
	ds_read_b128 v[196:199], v154 offset:35840
	ds_read_b128 v[200:203], v154 offset:36864
	ds_read_b128 v[204:207], v154 offset:37888
	ds_read_b128 v[208:211], v154 offset:38912
	ds_read_b128 v[212:215], v154 offset:39936
	global_load_lds_dwordx4 v130, s[92:93]
	s_mov_b32 m0, s70
	s_nop 0
	global_load_lds_dwordx4 v134, s[92:93]
	s_waitcnt vmcnt(8)
	s_waitcnt lgkmcnt(0)
	s_barrier
	s_setprio 1
	s_waitcnt lgkmcnt(0)
	v_mfma_f32_16x16x32_bf16 v[126:129], v[146:149], v[184:187], v[126:129]
	v_mfma_f32_16x16x32_bf16 v[122:125], v[160:163], v[184:187], v[122:125]
	v_mfma_f32_16x16x32_bf16 v[118:121], v[146:149], v[192:195], v[118:121]
	v_mfma_f32_16x16x32_bf16 v[114:117], v[160:163], v[192:195], v[114:117]
	v_mfma_f32_16x16x32_bf16 v[110:113], v[146:149], v[200:203], v[110:113]
	v_mfma_f32_16x16x32_bf16 v[106:109], v[160:163], v[200:203], v[106:109]
	v_mfma_f32_16x16x32_bf16 v[102:105], v[146:149], v[208:211], v[102:105]
	v_mfma_f32_16x16x32_bf16 v[98:101], v[160:163], v[208:211], v[98:101]
	v_mfma_f32_16x16x32_bf16 v[126:129], v[156:159], v[188:191], v[126:129]
	v_mfma_f32_16x16x32_bf16 v[122:125], v[164:167], v[188:191], v[122:125]
	v_mfma_f32_16x16x32_bf16 v[118:121], v[156:159], v[196:199], v[118:121]
	v_mfma_f32_16x16x32_bf16 v[114:117], v[164:167], v[196:199], v[114:117]
	v_mfma_f32_16x16x32_bf16 v[110:113], v[156:159], v[204:207], v[110:113]
	v_mfma_f32_16x16x32_bf16 v[106:109], v[164:167], v[204:207], v[106:109]
	v_mfma_f32_16x16x32_bf16 v[102:105], v[156:159], v[212:215], v[102:105]
	v_mfma_f32_16x16x32_bf16 v[98:101], v[164:167], v[212:215], v[98:101]
	s_setprio 0
	s_setprio 1
	v_mfma_f32_16x16x32_bf16 v[62:65], v[168:171], v[184:187], v[62:65]
	v_mfma_f32_16x16x32_bf16 v[58:61], v[176:179], v[184:187], v[58:61]
	v_mfma_f32_16x16x32_bf16 v[54:57], v[168:171], v[192:195], v[54:57]
	v_mfma_f32_16x16x32_bf16 v[50:53], v[176:179], v[192:195], v[50:53]
	v_mfma_f32_16x16x32_bf16 v[46:49], v[168:171], v[200:203], v[46:49]
	v_mfma_f32_16x16x32_bf16 v[42:45], v[176:179], v[200:203], v[42:45]
	v_mfma_f32_16x16x32_bf16 v[38:41], v[168:171], v[208:211], v[38:41]
	v_mfma_f32_16x16x32_bf16 v[34:37], v[176:179], v[208:211], v[34:37]
	v_mfma_f32_16x16x32_bf16 v[62:65], v[172:175], v[188:191], v[62:65]
	v_mfma_f32_16x16x32_bf16 v[58:61], v[180:183], v[188:191], v[58:61]
	v_mfma_f32_16x16x32_bf16 v[54:57], v[172:175], v[196:199], v[54:57]
	v_mfma_f32_16x16x32_bf16 v[50:53], v[180:183], v[196:199], v[50:53]
	v_mfma_f32_16x16x32_bf16 v[46:49], v[172:175], v[204:207], v[46:49]
	v_mfma_f32_16x16x32_bf16 v[42:45], v[180:183], v[204:207], v[42:45]
	v_mfma_f32_16x16x32_bf16 v[38:41], v[172:175], v[212:215], v[38:41]
	v_mfma_f32_16x16x32_bf16 v[34:37], v[180:183], v[212:215], v[34:37]
	s_setprio 0
	s_barrier
	s_add_i32 s3, s3, s12
	s_add_u32 s98, s90, 0x80
	s_addc_u32 s99, s91, 0
	s_add_u32 s100, s92, 0xfffc0080
	s_addc_u32 s101, s93, -1
	s_mov_b32 m0, s3
	ds_read_b128 v[184:187], v154 offset:49152
	ds_read_b128 v[188:191], v154 offset:50176
	ds_read_b128 v[192:195], v154 offset:51200
	ds_read_b128 v[196:199], v154 offset:52224
	ds_read_b128 v[200:203], v154 offset:53248
	ds_read_b128 v[204:207], v154 offset:54272
	ds_read_b128 v[208:211], v154 offset:55296
	ds_read_b128 v[212:215], v154 offset:56320
	global_load_lds_dwordx4 v132, s[98:99]
	s_add_i32 m0, s3, 0x2000
	s_add_u32 s90, s90, 0x40080
	s_addc_u32 s91, s91, 0
	s_add_i32 s3, s97, s12
	global_load_lds_dwordx4 v136, s[98:99]
	s_mov_b32 m0, s3
	s_nop 0
	global_load_lds_dwordx4 v132, s[90:91]
	s_add_i32 m0, s3, 0x2000
	s_nop 0
	global_load_lds_dwordx4 v136, s[90:91]
	s_mov_b32 m0, s71
	s_nop 0
	global_load_lds_dwordx4 v130, s[100:101]
	s_mov_b32 m0, s72
	s_nop 0
	global_load_lds_dwordx4 v134, s[100:101]
	s_waitcnt vmcnt(8)
	s_waitcnt lgkmcnt(0)
	s_barrier
	s_setprio 1
	s_waitcnt lgkmcnt(0)
	v_mfma_f32_16x16x32_bf16 v[94:97], v[146:149], v[184:187], v[94:97]
	s_add_i32 s96, s96, 2
	s_add_u32 s88, s88, 0x100
	s_addc_u32 s89, s89, 0
	s_add_u32 s81, s81, 0x100
	s_addc_u32 s87, s87, 0
	s_cmp_gt_u32 s96, 13
	v_mfma_f32_16x16x32_bf16 v[90:93], v[160:163], v[184:187], v[90:93]
	v_mfma_f32_16x16x32_bf16 v[86:89], v[146:149], v[192:195], v[86:89]
	v_mfma_f32_16x16x32_bf16 v[82:85], v[160:163], v[192:195], v[82:85]
	v_mfma_f32_16x16x32_bf16 v[78:81], v[146:149], v[200:203], v[78:81]
	v_mfma_f32_16x16x32_bf16 v[74:77], v[160:163], v[200:203], v[74:77]
	v_mfma_f32_16x16x32_bf16 v[70:73], v[146:149], v[208:211], v[70:73]
	v_mfma_f32_16x16x32_bf16 v[66:69], v[160:163], v[208:211], v[66:69]
	v_mfma_f32_16x16x32_bf16 v[94:97], v[156:159], v[188:191], v[94:97]
	v_mfma_f32_16x16x32_bf16 v[90:93], v[164:167], v[188:191], v[90:93]
	v_mfma_f32_16x16x32_bf16 v[86:89], v[156:159], v[196:199], v[86:89]
	v_mfma_f32_16x16x32_bf16 v[82:85], v[164:167], v[196:199], v[82:85]
	v_mfma_f32_16x16x32_bf16 v[78:81], v[156:159], v[204:207], v[78:81]
	v_mfma_f32_16x16x32_bf16 v[74:77], v[164:167], v[204:207], v[74:77]
	v_mfma_f32_16x16x32_bf16 v[70:73], v[156:159], v[212:215], v[70:73]
	v_mfma_f32_16x16x32_bf16 v[66:69], v[164:167], v[212:215], v[66:69]
	s_setprio 0
	s_setprio 1
	v_mfma_f32_16x16x32_bf16 v[30:33], v[168:171], v[184:187], v[30:33]
	v_mfma_f32_16x16x32_bf16 v[26:29], v[176:179], v[184:187], v[26:29]
	v_mfma_f32_16x16x32_bf16 v[22:25], v[168:171], v[192:195], v[22:25]
	v_mfma_f32_16x16x32_bf16 v[18:21], v[176:179], v[192:195], v[18:21]
	v_mfma_f32_16x16x32_bf16 v[14:17], v[168:171], v[200:203], v[14:17]
	v_mfma_f32_16x16x32_bf16 v[10:13], v[176:179], v[200:203], v[10:13]
	v_mfma_f32_16x16x32_bf16 v[6:9], v[168:171], v[208:211], v[6:9]
	v_mfma_f32_16x16x32_bf16 v[2:5], v[176:179], v[208:211], v[2:5]
	v_mfma_f32_16x16x32_bf16 v[30:33], v[172:175], v[188:191], v[30:33]
	v_mfma_f32_16x16x32_bf16 v[26:29], v[180:183], v[188:191], v[26:29]
	v_mfma_f32_16x16x32_bf16 v[22:25], v[172:175], v[196:199], v[22:25]
	v_mfma_f32_16x16x32_bf16 v[18:21], v[180:183], v[196:199], v[18:21]
	v_mfma_f32_16x16x32_bf16 v[14:17], v[172:175], v[204:207], v[14:17]
	v_mfma_f32_16x16x32_bf16 v[10:13], v[180:183], v[204:207], v[10:13]
	v_mfma_f32_16x16x32_bf16 v[6:9], v[172:175], v[212:215], v[6:9]
	v_mfma_f32_16x16x32_bf16 v[2:5], v[180:183], v[212:215], v[2:5]
	s_setprio 0
	s_barrier
	s_cbranch_scc0 .LBB0_270
	s_and_b64 vcc, exec, s[56:57]
	s_cbranch_vccz .LBB0_273
	s_barrier
